# m1 FoX body + epilogue-wait decoupling + P0 loop-top drain moved + hand-written P4 row loop (2-row prefetch) + sample-unit Q drain removed
# baseline (speedup 1.0000x reference)
; template <int MODE> ...
;     asm volatile("" : "+v"(lane));
;     const int r32 = lane & 31, hi = lane >> 5;
;     LAS unsigned char* st = stage0 + wave * 8704;
;     bf16x8 qf[4];
; #pragma unroll
;     for (int d0 = 0; d0 < 4; ++d0) qf[d0] = *(const bf16x8*)(Qrow + r32 * 64 + d0 * 16 + hi * 8);
;     const int skey = lane >> 3, sch = lane & 7;
;     const int kwA = skey * 128 + ((sch ^ (skey >> 1)) << 4), kwB = skey * 128 + ((sch ^ ((skey >> 1) + 4)) << 4);
;     const int vw0 = 4096 + (sch >> 2) * 512 + skey * 64 + (sch & 3) * 16;
;     const bf16_t* kg = Kb + lane * 8;
;     const bf16_t* vg = Vb + lane * 8;
;     const unsigned vaddr = (unsigned)(unsigned long)(st + 4096) + v_lane_off(lane);
;     u32x4 kr[4], vr[4];
; #pragma unroll
;     for (int i = 0; i < 4; ++i) { kr[i] = *(const u32x4*)(kg + (size_t)(kb0 * 32 + 8 * i) * 64); vr[i] = *(const u32x4*)(vg + (size_t)(kb0 * 32 + 8 * i) * 64); }
;     const float cq = (MODE == 1) ? tab[qpos0 + r32] : 0.f;
;     const float cfar = (MODE == 0) ? tab[256] : 0.f;
;     St S; st_init(S);
;     asm volatile("" :: "v"(qf[0]), "v"(qf[1]), "v"(qf[2]), "v"(qf[3]));
; __device__ __forceinline__ void phase2(const Params& P, LAS unsigned char* lds, int tid, int lane, int wave) {
;     ...
;         if (vb < 128) {
;             const int mode = vb < 64, bs = (vb & 63) >> 3;
;             const size_t qrow = (size_t)MP + bs * NST;
;             const int L = mode ? LBS_LEN : LAS_LEN, nb = L / 32;
;             const size_t kvo = (size_t)(bs * 8 + h) * L * 64;
;             const size_t qgo = ((size_t)(32 * 8 + h) * 2048 + bs * NST) * 64;
;             const int kb0 = (wave * nb) >> 3, kb1 = ((wave + 1) * nb) >> 3;
;             const bf16_t* Qrow = (const bf16_t*)(P.ws + WS_SEG + (size_t)(mode ? 4 : 0) * SEG_STRIDE) + qgo;
;             const bf16_t* Grow = (const bf16_t*)(P.ws + WS_SEG + (size_t)(mode ? 7 : 3) * SEG_STRIDE) + qgo;
;             bf16_t* Yrow = (bf16_t*)(P.ws + WS_H) + qrow * 1024 + (mode ? 512 : 0) + h * 64;
;             if (mode) att::split_unit<1>(Qrow, (const bf16_t*)(P.ws + WS_KBS) + kvo, (const bf16_t*)(P.ws + WS_VBS) + kvo, kb0, kb1, nb - 1, PAST, c2s, Yrow, Grow, work, wave, lane);
;             else      att::split_unit<0>(Qrow, (const bf16_t*)(P.ws + WS_KAS) + kvo, (const bf16_t*)(P.ws + WS_VAS) + kvo, kb0, kb1, -1, LAC, rb2, Yrow, Grow, work, wave, lane);
.LBB0_547:
	s_andn2_b64 vcc, exec, s[0:1]
	s_cbranch_vccnz .LBB0_595
	s_lshl_b32 s0, s96, 2
	s_and_b32 s4, s0, 0xe0
	s_and_b64 s[0:1], s[8:9], exec
	s_movk_i32 s0, 0x220
	s_cselect_b32 s0, s0, 0x820
	s_lshl_b32 s1, s96, 6
	s_and_b32 s7, s1, 0xfc0
	s_lshr_b32 s3, s0, 5
	s_mul_i32 s7, s7, s0
	s_lshl_b32 s0, s14, 18
	s_lshl_b32 s1, s4, 7
	s_or_b32 s5, s1, s0
	s_mul_i32 s0, s3, s86
	s_lshr_b32 s6, s0, 3
	s_add_i32 s0, s0, s3
	s_lshr_b32 s2, s0, 3
	s_and_b64 s[0:1], s[8:9], exec
	s_cselect_b32 s0, 0, 0x10800000
	v_readlane_b32 s10, v241, 42
	s_add_u32 s0, s10, s0
	v_readlane_b32 s11, v241, 43
	s_addc_u32 s1, s11, 0
	s_bitset1_b32 s5, 26
	s_add_u32 s16, s0, s5
	s_addc_u32 s17, s1, 0
	s_and_b64 s[0:1], s[8:9], exec
	s_cselect_b32 s0, s33, 0x1ce00000
	s_add_u32 s0, s10, s0
	s_addc_u32 s1, s11, 0
	s_add_u32 s10, s0, s5
	s_addc_u32 s11, s1, 0
	s_lshl_b32 s0, s4, 11
	s_add_u32 s4, s92, s0
	s_addc_u32 s5, s93, 0
	s_and_b64 s[0:1], s[8:9], exec
	s_cselect_b32 s0, 0, 0x400
	s_add_u32 s0, s4, s0
	s_addc_u32 s1, s5, 0
	s_lshl_b32 s4, s14, 7
	s_add_u32 s0, s0, s4
	s_addc_u32 s1, s1, 0
	s_add_u32 s8, s0, 0xc000000
	s_addc_u32 s9, s1, 0
	s_andn2_b64 vcc, exec, s[24:25]
	s_mov_b64 s[0:1], -1
	s_cbranch_vccnz .LBB0_570
	v_mov_b32_e32 v105, v126
	s_cmp_lt_u32 s6, s2
	v_and_b32_e32 v104, 31, v105
	v_ashrrev_i32_e32 v2, 5, v105
	v_lshlrev_b32_e32 v0, 7, v104
	v_lshlrev_b32_e32 v6, 3, v2
	v_lshl_add_u64 v[4:5], s[16:17], 0, v[0:1]
	v_ashrrev_i32_e32 v7, 31, v6
	v_lshl_add_u64 v[4:5], v[6:7], 1, v[4:5]
	global_load_dwordx4 v[50:53], v[4:5], off
	global_load_dwordx4 v[54:57], v[4:5], off offset:32
	global_load_dwordx4 v[58:61], v[4:5], off offset:64
	global_load_dwordx4 v[62:65], v[4:5], off offset:96
	v_lshl_add_u32 v0, v104, 2, 0
	ds_read_b32 v106, v0 offset:16384
	v_lshlrev_b32_e32 v0, 2, v2
	s_cbranch_scc1 .LBB0_551
	v_lshlrev_b32_e32 v34, 2, v2
	s_mov_b64 s[0:1], 0

; __device__ __forceinline__ unsigned v_lane_off(int lane) { return (unsigned)((4 * (lane >> 5) + ((lane & 15) >> 2)) * 64 + ((lane >> 4) & 1) * 32 + (lane & 3) * 8); }
; template <int MODE> ...
;     ...
;     bf16x8 qf[4];
; #pragma unroll
;     for (int d0 = 0; d0 < 4; ++d0) qf[d0] = *(const bf16x8*)(Qrow + r32 * 64 + d0 * 16 + hi * 8);
;     const int skey = lane >> 3, sch = lane & 7;
;     const int kwA = skey * 128 + ((sch ^ (skey >> 1)) << 4), kwB = skey * 128 + ((sch ^ ((skey >> 1) + 4)) << 4);
;     const int vw0 = 4096 + (sch >> 2) * 512 + skey * 64 + (sch & 3) * 16;
;     const bf16_t* kg = Kb + lane * 8;
;     const bf16_t* vg = Vb + lane * 8;
;     const unsigned vaddr = (unsigned)(unsigned long)(st + 4096) + v_lane_off(lane);
;     u32x4 kr[4], vr[4];
; #pragma unroll
;     for (int i = 0; i < 4; ++i) { kr[i] = *(const u32x4*)(kg + (size_t)(kb0 * 32 + 8 * i) * 64); vr[i] = *(const u32x4*)(vg + (size_t)(kb0 * 32 + 8 * i) * 64); }
;     const float cq = (MODE == 1) ? tab[qpos0 + r32] : 0.f;
;     const float cfar = (MODE == 0) ? tab[256] : 0.f;
.LBB0_570:
	s_lshl_b32 s34, s14, 6
	s_mov_b32 s35, s13
	s_and_b64 vcc, exec, s[0:1]
	s_cbranch_vccz .LBB0_595
	v_mov_b32_e32 v124, v126
	s_mov_b64 s[0:1], -1
	v_and_b32_e32 v122, 31, v124
	v_ashrrev_i32_e32 v2, 5, v124
	v_lshlrev_b32_e32 v0, 7, v122
	v_lshlrev_b32_e32 v6, 3, v2
	v_lshl_add_u64 v[4:5], s[16:17], 0, v[0:1]
	v_ashrrev_i32_e32 v7, 31, v6
	v_lshl_add_u64 v[4:5], v[6:7], 1, v[4:5]
	global_load_dwordx4 v[50:53], v[4:5], off
	global_load_dwordx4 v[54:57], v[4:5], off offset:32
	global_load_dwordx4 v[58:61], v[4:5], off offset:64
	global_load_dwordx4 v[62:65], v[4:5], off offset:96
	ds_read_b32 v0, v1 offset:17664
	s_cmp_lt_u32 s6, s2
	v_lshlrev_b32_e32 v123, 2, v2
	s_cbranch_scc1 .LBB0_573
	v_lshlrev_b32_e32 v34, 2, v2
	s_mov_b64 s[0:1], 0

; __device__ __forceinline__ float bf_lo(unsigned w) { return __uint_as_float(w << 16); }
; __device__ __forceinline__ float bf_hi(unsigned w) { return __uint_as_float(w & 0xffff0000u); }
; __device__ __forceinline__ void phase4(const Params& P, int lane, int wave) {
;     const int gw = blockIdx.x * 8 + wave, NGW = gridDim.x * 8;
;     const bf16_t* mo = (const bf16_t*)(P.ws + WS_SEG);
;     f32x4 g4[4];
; #pragma unroll
;     for (int j = 0; j < 4; ++j) g4[j] = *(const f32x4*)(P.fgain + 4 * lane + 256 * j);
;     f32x4 v[4]; u32x2 mv[4];
;     int m = gw;
;     if (m < MT) {
;         const float* xrow = (m < MP) ? P.xp + (size_t)m * 1024 : P.xs + (size_t)(m - MP) * 1024;
; #pragma unroll
;         for (int j = 0; j < 4; ++j) { v[j] = *(const f32x4*)(xrow + 4 * lane + 256 * j); mv[j] = *(const u32x2*)(mo + (size_t)m * 1024 + 4 * lane + 256 * j); }
;     }
;     for (; m < MT; m += NGW) {
;         f32x4 r[4]; float ss = 0.f;
; #pragma unroll
;         for (int j = 0; j < 4; ++j) {
;             r[j][0] = v[j][0] + bf_lo(mv[j].x); r[j][1] = v[j][1] + bf_hi(mv[j].x); r[j][2] = v[j][2] + bf_lo(mv[j].y); r[j][3] = v[j][3] + bf_hi(mv[j].y);
;             ss += (r[j][0] * r[j][0] + r[j][1] * r[j][1]) + (r[j][2] * r[j][2] + r[j][3] * r[j][3]);
;         }
;         const int mn = m + NGW;
;         if (mn < MT) {
;             const float* xrow = (mn < MP) ? P.xp + (size_t)mn * 1024 : P.xs + (size_t)(mn - MP) * 1024;
; #pragma unroll
;             for (int j = 0; j < 4; ++j) { v[j] = *(const f32x4*)(xrow + 4 * lane + 256 * j); mv[j] = *(const u32x2*)(mo + (size_t)mn * 1024 + 4 * lane + 256 * j); }
;         }
.LBB0_793:
	s_or_b64 exec, exec, s[0:1]
	v_readlane_b32 s0, v241, 12
	v_readlane_b32 s1, v241, 13
	s_andn2_b64 vcc, exec, s[0:1]
	s_waitcnt lgkmcnt(0)
	s_barrier
	s_cbranch_vccnz .LBB0_806
	v_mbcnt_hi_u32_b32 v82, -1, v179
	v_lshlrev_b32_e32 v80, 4, v82
	v_lshlrev_b32_e32 v81, 3, v82
	global_load_dwordx4 v[0:3], v80, s[88:89]
	global_load_dwordx4 v[4:7], v80, s[88:89] offset:1024
	global_load_dwordx4 v[8:11], v80, s[88:89] offset:2048
	global_load_dwordx4 v[12:15], v80, s[88:89] offset:3072
	v_xor_b32_e32 v72, 1, v82
	v_lshlrev_b32_e32 v72, 2, v72
	v_xor_b32_e32 v73, 2, v82
	v_lshlrev_b32_e32 v73, 2, v73
	v_xor_b32_e32 v74, 4, v82
	v_lshlrev_b32_e32 v74, 2, v74
	v_xor_b32_e32 v75, 8, v82
	v_lshlrev_b32_e32 v75, 2, v75
	v_xor_b32_e32 v76, 16, v82
	v_lshlrev_b32_e32 v76, 2, v76
	v_xor_b32_e32 v77, 32, v82
	v_lshlrev_b32_e32 v77, 2, v77
	v_mov_b32_e32 v70, 0x358637bd
	v_mov_b32_e32 v71, 0x260
	s_mov_b32 s2, 0xf800000
	v_readlane_b32 s8, v241, 10
	s_cmp_lt_u32 s8, 0x100
	s_cselect_b32 s9, 33, 32
	s_add_i32 s10, s9, -1
	s_mov_b32 s11, 0
	s_mul_i32 s16, s11, s84
	s_add_i32 s16, s16, s8
	s_lshl_b32 s17, s16, 11
	s_add_u32 s14, s4, s17
	s_addc_u32 s15, s5, 0
	s_add_i32 s18, s16, 0xffff0000
	s_cmp_lt_u32 s16, 0x10000
	s_cselect_b32 s18, s16, s18
	s_cselect_b32 s12, s68, s70
	s_cselect_b32 s13, s69, s71
	s_lshr_b32 s19, s18, 20
	s_lshl_b32 s18, s18, 12
	s_add_u32 s12, s12, s18
	s_addc_u32 s13, s13, s19
	global_load_dwordx4 v[16:19], v80, s[12:13]
	global_load_dwordx4 v[20:23], v80, s[12:13] offset:1024
	global_load_dwordx4 v[24:27], v80, s[12:13] offset:2048
	global_load_dwordx4 v[28:31], v80, s[12:13] offset:3072
	global_load_dwordx2 v[32:33], v81, s[14:15]
	global_load_dwordx2 v[34:35], v81, s[14:15] offset:512
	global_load_dwordx2 v[36:37], v81, s[14:15] offset:1024
	global_load_dwordx2 v[38:39], v81, s[14:15] offset:1536
	s_min_u32 s20, 1, s10
	s_mul_i32 s16, s20, s84
	s_add_i32 s16, s16, s8
	s_lshl_b32 s17, s16, 11
	s_add_u32 s14, s4, s17
	s_addc_u32 s15, s5, 0
	s_add_i32 s18, s16, 0xffff0000
	s_cmp_lt_u32 s16, 0x10000
	s_cselect_b32 s18, s16, s18
	s_cselect_b32 s12, s68, s70
	s_cselect_b32 s13, s69, s71
	s_lshr_b32 s19, s18, 20
	s_lshl_b32 s18, s18, 12
	s_add_u32 s12, s12, s18
	s_addc_u32 s13, s13, s19
	global_load_dwordx4 v[40:43], v80, s[12:13]
	global_load_dwordx4 v[44:47], v80, s[12:13] offset:1024
	global_load_dwordx4 v[48:51], v80, s[12:13] offset:2048
	global_load_dwordx4 v[52:55], v80, s[12:13] offset:3072
	global_load_dwordx2 v[56:57], v81, s[14:15]
	global_load_dwordx2 v[58:59], v81, s[14:15] offset:512
	global_load_dwordx2 v[60:61], v81, s[14:15] offset:1024
	global_load_dwordx2 v[62:63], v81, s[14:15] offset:1536
.Lp4_loop:
	s_add_i32 s20, s11, 2
	s_min_u32 s20, s20, s10
	s_mul_i32 s16, s20, s84
	s_add_i32 s16, s16, s8
	s_lshl_b32 s17, s16, 11
	s_add_u32 s14, s4, s17
	s_addc_u32 s15, s5, 0
	s_add_i32 s18, s16, 0xffff0000
	s_cmp_lt_u32 s16, 0x10000
	s_cselect_b32 s18, s16, s18
	s_cselect_b32 s12, s68, s70
	s_cselect_b32 s13, s69, s71
	s_lshr_b32 s19, s18, 20
	s_lshl_b32 s18, s18, 12
	s_add_u32 s12, s12, s18
	s_addc_u32 s13, s13, s19
	global_load_dwordx4 v[88:91], v80, s[12:13]
	global_load_dwordx4 v[92:95], v80, s[12:13] offset:1024
	global_load_dwordx4 v[96:99], v80, s[12:13] offset:2048
	global_load_dwordx4 v[100:103], v80, s[12:13] offset:3072
	global_load_dwordx2 v[104:105], v81, s[14:15]
	global_load_dwordx2 v[106:107], v81, s[14:15] offset:512
	global_load_dwordx2 v[108:109], v81, s[14:15] offset:1024
	global_load_dwordx2 v[110:111], v81, s[14:15] offset:1536
	s_mul_i32 s16, s11, s84
	s_add_i32 s16, s16, s8
	s_lshr_b32 s19, s16, 20
	s_lshl_b32 s18, s16, 12
	s_add_u32 s0, s90, s18
	s_addc_u32 s1, s91, s19
	s_waitcnt vmcnt(16)
	v_lshlrev_b32_e32 v64, 16, v32
	v_and_b32_e32 v65, 0xffff0000, v32
	v_add_f32_e32 v16, v16, v64
	v_add_f32_e32 v17, v17, v65
	v_lshlrev_b32_e32 v64, 16, v33
	v_and_b32_e32 v65, 0xffff0000, v33
	v_add_f32_e32 v18, v18, v64
	v_add_f32_e32 v19, v19, v65
	v_lshlrev_b32_e32 v64, 16, v34
	v_and_b32_e32 v65, 0xffff0000, v34
	v_add_f32_e32 v20, v20, v64
	v_add_f32_e32 v21, v21, v65
	v_lshlrev_b32_e32 v64, 16, v35
	v_and_b32_e32 v65, 0xffff0000, v35
	v_add_f32_e32 v22, v22, v64
	v_add_f32_e32 v23, v23, v65
	v_lshlrev_b32_e32 v64, 16, v36
	v_and_b32_e32 v65, 0xffff0000, v36
	v_add_f32_e32 v24, v24, v64
	v_add_f32_e32 v25, v25, v65
	v_lshlrev_b32_e32 v64, 16, v37
	v_and_b32_e32 v65, 0xffff0000, v37
	v_add_f32_e32 v26, v26, v64
	v_add_f32_e32 v27, v27, v65
	v_lshlrev_b32_e32 v64, 16, v38
	v_and_b32_e32 v65, 0xffff0000, v38
	v_add_f32_e32 v28, v28, v64
	v_add_f32_e32 v29, v29, v65
	v_lshlrev_b32_e32 v64, 16, v39
	v_and_b32_e32 v65, 0xffff0000, v39
	v_add_f32_e32 v30, v30, v64
	v_add_f32_e32 v31, v31, v65
	v_mul_f32_e32 v64, v16, v16
	v_mul_f32_e32 v65, v17, v17
	v_mul_f32_e32 v66, v18, v18
	v_mul_f32_e32 v67, v19, v19
	v_add_f32_e32 v64, v64, v65
	v_add_f32_e32 v66, v66, v67
	v_add_f32_e32 v68, v64, v66
	v_mul_f32_e32 v64, v20, v20
	v_mul_f32_e32 v65, v21, v21
	v_mul_f32_e32 v66, v22, v22
	v_mul_f32_e32 v67, v23, v23
	v_add_f32_e32 v64, v64, v65
	v_add_f32_e32 v66, v66, v67
	v_add_f32_e32 v64, v64, v66
	v_add_f32_e32 v68, v68, v64
	v_mul_f32_e32 v64, v24, v24
	v_mul_f32_e32 v65, v25, v25
	v_mul_f32_e32 v66, v26, v26
	v_mul_f32_e32 v67, v27, v27
	v_add_f32_e32 v64, v64, v65
	v_add_f32_e32 v66, v66, v67
	v_add_f32_e32 v64, v64, v66
	v_add_f32_e32 v68, v68, v64
	v_mul_f32_e32 v64, v28, v28
	v_mul_f32_e32 v65, v29, v29
	v_mul_f32_e32 v66, v30, v30
	v_mul_f32_e32 v67, v31, v31
	v_add_f32_e32 v64, v64, v65
	v_add_f32_e32 v66, v66, v67
	v_add_f32_e32 v64, v64, v66
	v_add_f32_e32 v68, v68, v64
	ds_bpermute_b32 v69, v72, v68
	s_waitcnt lgkmcnt(0)
; __device__ __forceinline__ float bf_lo(unsigned w) { return __uint_as_float(w << 16); }
; __device__ __forceinline__ float bf_hi(unsigned w) { return __uint_as_float(w & 0xffff0000u); }
; __device__ __forceinline__ void phase4(const Params& P, int lane, int wave) {
;     ...
; #pragma unroll
;         for (int j = 0; j < 4; ++j) {
;             r[j][0] = v[j][0] + bf_lo(mv[j].x); r[j][1] = v[j][1] + bf_hi(mv[j].x); r[j][2] = v[j][2] + bf_lo(mv[j].y); r[j][3] = v[j][3] + bf_hi(mv[j].y);
;             ss += (r[j][0] * r[j][0] + r[j][1] * r[j][1]) + (r[j][2] * r[j][2] + r[j][3] * r[j][3]);
;         }
;         const int mn = m + NGW;
;         if (mn < MT) {
;             const float* xrow = (mn < MP) ? P.xp + (size_t)mn * 1024 : P.xs + (size_t)(mn - MP) * 1024;
; #pragma unroll
;             for (int j = 0; j < 4; ++j) { v[j] = *(const f32x4*)(xrow + 4 * lane + 256 * j); mv[j] = *(const u32x2*)(mo + (size_t)mn * 1024 + 4 * lane + 256 * j); }
;         }
;         ss = wave_sum(ss);
;         const float rstd = 1.0f / sqrtf(ss * (1.0f / 1024.0f) + RMS_EPS);
;         float* row = P.out + (size_t)m * 1024;
; #pragma unroll
;         for (int j = 0; j < 4; ++j) *(f32x4*)(row + 4 * lane + 256 * j) = r[j] * rstd * g4[j];
	v_add_f32_e32 v68, v68, v69
	ds_bpermute_b32 v69, v73, v68
	s_waitcnt lgkmcnt(0)
	v_add_f32_e32 v68, v68, v69
	ds_bpermute_b32 v69, v74, v68
	s_waitcnt lgkmcnt(0)
	v_add_f32_e32 v68, v68, v69
	ds_bpermute_b32 v69, v75, v68
	s_waitcnt lgkmcnt(0)
	v_add_f32_e32 v68, v68, v69
	ds_bpermute_b32 v69, v76, v68
	s_waitcnt lgkmcnt(0)
	v_add_f32_e32 v68, v68, v69
	ds_bpermute_b32 v69, v77, v68
	s_waitcnt lgkmcnt(0)
	v_add_f32_e32 v68, v68, v69
	v_fmamk_f32 v68, v68, 0x3a800000, v70
	v_mul_f32_e32 v69, 0x4f800000, v68
	v_cmp_gt_f32_e32 vcc, s2, v68
	s_nop 1
	v_cndmask_b32_e32 v68, v68, v69, vcc
	v_sqrt_f32_e32 v69, v68
	s_nop 0
	v_add_u32_e32 v64, -1, v69
	v_fma_f32 v65, -v64, v69, v68
	v_cmp_ge_f32_e64 s[6:7], 0, v65
	v_add_u32_e32 v65, 1, v69
	s_nop 0
	v_cndmask_b32_e64 v64, v69, v64, s[6:7]
	v_fma_f32 v69, -v65, v69, v68
	v_cmp_lt_f32_e64 s[6:7], 0, v69
	s_nop 1
	v_cndmask_b32_e64 v69, v64, v65, s[6:7]
	v_mul_f32_e32 v64, 0x37800000, v69
	v_cndmask_b32_e32 v69, v69, v64, vcc
	v_cmp_class_f32_e32 vcc, v68, v71
	s_nop 1
	v_cndmask_b32_e32 v68, v69, v68, vcc
	v_div_scale_f32 v69, s[6:7], v68, v68, 1.0
	v_rcp_f32_e32 v64, v69
	s_nop 0
	v_fma_f32 v65, -v69, v64, 1.0
	v_fmac_f32_e32 v64, v65, v64
	v_div_scale_f32 v65, vcc, 1.0, v68, 1.0
	v_mul_f32_e32 v66, v65, v64
	v_fma_f32 v67, -v69, v66, v65
	v_fmac_f32_e32 v66, v67, v64
	v_fma_f32 v69, -v69, v66, v65
	v_div_fmas_f32 v69, v69, v64, v66
	v_div_fixup_f32 v68, v69, v68, 1.0
	v_mul_f32_e32 v16, v16, v68
	v_mul_f32_e32 v17, v17, v68
	v_mul_f32_e32 v18, v18, v68
	v_mul_f32_e32 v19, v19, v68
	v_mul_f32_e32 v16, v0, v16
	v_mul_f32_e32 v17, v1, v17
	v_mul_f32_e32 v18, v2, v18
	v_mul_f32_e32 v19, v3, v19
	global_store_dwordx4 v80, v[16:19], s[0:1]
	v_mul_f32_e32 v20, v20, v68
	v_mul_f32_e32 v21, v21, v68
	v_mul_f32_e32 v22, v22, v68
	v_mul_f32_e32 v23, v23, v68
	v_mul_f32_e32 v20, v4, v20
	v_mul_f32_e32 v21, v5, v21
	v_mul_f32_e32 v22, v6, v22
	v_mul_f32_e32 v23, v7, v23
	global_store_dwordx4 v80, v[20:23], s[0:1] offset:1024
	v_mul_f32_e32 v24, v24, v68
	v_mul_f32_e32 v25, v25, v68
	v_mul_f32_e32 v26, v26, v68
	v_mul_f32_e32 v27, v27, v68
	v_mul_f32_e32 v24, v8, v24
	v_mul_f32_e32 v25, v9, v25
	v_mul_f32_e32 v26, v10, v26
	v_mul_f32_e32 v27, v11, v27
	global_store_dwordx4 v80, v[24:27], s[0:1] offset:2048
	v_mul_f32_e32 v28, v28, v68
	v_mul_f32_e32 v29, v29, v68
	v_mul_f32_e32 v30, v30, v68
	v_mul_f32_e32 v31, v31, v68
	v_mul_f32_e32 v28, v12, v28
	v_mul_f32_e32 v29, v13, v29
	v_mul_f32_e32 v30, v14, v30
	v_mul_f32_e32 v31, v15, v31
	global_store_dwordx4 v80, v[28:31], s[0:1] offset:3072
	s_add_i32 s11, s11, 1
	s_cmp_ge_u32 s11, s9
	s_cbranch_scc1 .LBB0_806
	s_add_i32 s20, s11, 2
	s_min_u32 s20, s20, s10
	s_mul_i32 s16, s20, s84
	s_add_i32 s16, s16, s8
	s_lshl_b32 s17, s16, 11
	s_add_u32 s14, s4, s17
	s_addc_u32 s15, s5, 0
	s_add_i32 s18, s16, 0xffff0000
	s_cmp_lt_u32 s16, 0x10000
	s_cselect_b32 s18, s16, s18
	s_cselect_b32 s12, s68, s70
	s_cselect_b32 s13, s69, s71
	s_lshr_b32 s19, s18, 20
	s_lshl_b32 s18, s18, 12
	s_add_u32 s12, s12, s18
	s_addc_u32 s13, s13, s19
	global_load_dwordx4 v[16:19], v80, s[12:13]
	global_load_dwordx4 v[20:23], v80, s[12:13] offset:1024
	global_load_dwordx4 v[24:27], v80, s[12:13] offset:2048
	global_load_dwordx4 v[28:31], v80, s[12:13] offset:3072
	global_load_dwordx2 v[32:33], v81, s[14:15]
	global_load_dwordx2 v[34:35], v81, s[14:15] offset:512
	global_load_dwordx2 v[36:37], v81, s[14:15] offset:1024
	global_load_dwordx2 v[38:39], v81, s[14:15] offset:1536
	s_mul_i32 s16, s11, s84
	s_add_i32 s16, s16, s8
	s_lshr_b32 s19, s16, 20
	s_lshl_b32 s18, s16, 12
	s_add_u32 s0, s90, s18
	s_addc_u32 s1, s91, s19
	s_waitcnt vmcnt(16)
	v_lshlrev_b32_e32 v64, 16, v56
	v_and_b32_e32 v65, 0xffff0000, v56
	v_add_f32_e32 v40, v40, v64
	v_add_f32_e32 v41, v41, v65
	v_lshlrev_b32_e32 v64, 16, v57
	v_and_b32_e32 v65, 0xffff0000, v57
	v_add_f32_e32 v42, v42, v64
	v_add_f32_e32 v43, v43, v65
	v_lshlrev_b32_e32 v64, 16, v58
	v_and_b32_e32 v65, 0xffff0000, v58
	v_add_f32_e32 v44, v44, v64
	v_add_f32_e32 v45, v45, v65
	v_lshlrev_b32_e32 v64, 16, v59
	v_and_b32_e32 v65, 0xffff0000, v59
	v_add_f32_e32 v46, v46, v64
	v_add_f32_e32 v47, v47, v65
	v_lshlrev_b32_e32 v64, 16, v60
	v_and_b32_e32 v65, 0xffff0000, v60
	v_add_f32_e32 v48, v48, v64
	v_add_f32_e32 v49, v49, v65
	v_lshlrev_b32_e32 v64, 16, v61
	v_and_b32_e32 v65, 0xffff0000, v61
	v_add_f32_e32 v50, v50, v64
	v_add_f32_e32 v51, v51, v65
	v_lshlrev_b32_e32 v64, 16, v62
	v_and_b32_e32 v65, 0xffff0000, v62
	v_add_f32_e32 v52, v52, v64
	v_add_f32_e32 v53, v53, v65
	v_lshlrev_b32_e32 v64, 16, v63
	v_and_b32_e32 v65, 0xffff0000, v63
	v_add_f32_e32 v54, v54, v64
	v_add_f32_e32 v55, v55, v65
	v_mul_f32_e32 v64, v40, v40
	v_mul_f32_e32 v65, v41, v41
	v_mul_f32_e32 v66, v42, v42
	v_mul_f32_e32 v67, v43, v43
	v_add_f32_e32 v64, v64, v65
	v_add_f32_e32 v66, v66, v67
	v_add_f32_e32 v68, v64, v66
	v_mul_f32_e32 v64, v44, v44
	v_mul_f32_e32 v65, v45, v45
	v_mul_f32_e32 v66, v46, v46
	v_mul_f32_e32 v67, v47, v47
	v_add_f32_e32 v64, v64, v65
	v_add_f32_e32 v66, v66, v67
	v_add_f32_e32 v64, v64, v66
	v_add_f32_e32 v68, v68, v64
	v_mul_f32_e32 v64, v48, v48
	v_mul_f32_e32 v65, v49, v49
	v_mul_f32_e32 v66, v50, v50
	v_mul_f32_e32 v67, v51, v51
	v_add_f32_e32 v64, v64, v65
	v_add_f32_e32 v66, v66, v67
	v_add_f32_e32 v64, v64, v66
	v_add_f32_e32 v68, v68, v64
	v_mul_f32_e32 v64, v52, v52
	v_mul_f32_e32 v65, v53, v53
	v_mul_f32_e32 v66, v54, v54
	v_mul_f32_e32 v67, v55, v55
	v_add_f32_e32 v64, v64, v65
	v_add_f32_e32 v66, v66, v67
	v_add_f32_e32 v64, v64, v66
	v_add_f32_e32 v68, v68, v64
	ds_bpermute_b32 v69, v72, v68
	s_waitcnt lgkmcnt(0)
; __device__ __forceinline__ void phase4(const Params& P, int lane, int wave) {
;     ...
;         ss = wave_sum(ss);
;         const float rstd = 1.0f / sqrtf(ss * (1.0f / 1024.0f) + RMS_EPS);
;         float* row = P.out + (size_t)m * 1024;
; #pragma unroll
;         for (int j = 0; j < 4; ++j) *(f32x4*)(row + 4 * lane + 256 * j) = r[j] * rstd * g4[j];
	v_add_f32_e32 v68, v68, v69
	ds_bpermute_b32 v69, v73, v68
	s_waitcnt lgkmcnt(0)
	v_add_f32_e32 v68, v68, v69
	ds_bpermute_b32 v69, v74, v68
	s_waitcnt lgkmcnt(0)
	v_add_f32_e32 v68, v68, v69
	ds_bpermute_b32 v69, v75, v68
	s_waitcnt lgkmcnt(0)
	v_add_f32_e32 v68, v68, v69
	ds_bpermute_b32 v69, v76, v68
	s_waitcnt lgkmcnt(0)
	v_add_f32_e32 v68, v68, v69
	ds_bpermute_b32 v69, v77, v68
	s_waitcnt lgkmcnt(0)
	v_add_f32_e32 v68, v68, v69
	v_fmamk_f32 v68, v68, 0x3a800000, v70
	v_mul_f32_e32 v69, 0x4f800000, v68
	v_cmp_gt_f32_e32 vcc, s2, v68
	s_nop 1
	v_cndmask_b32_e32 v68, v68, v69, vcc
	v_sqrt_f32_e32 v69, v68
	s_nop 0
	v_add_u32_e32 v64, -1, v69
	v_fma_f32 v65, -v64, v69, v68
	v_cmp_ge_f32_e64 s[6:7], 0, v65
	v_add_u32_e32 v65, 1, v69
	s_nop 0
	v_cndmask_b32_e64 v64, v69, v64, s[6:7]
	v_fma_f32 v69, -v65, v69, v68
	v_cmp_lt_f32_e64 s[6:7], 0, v69
	s_nop 1
	v_cndmask_b32_e64 v69, v64, v65, s[6:7]
	v_mul_f32_e32 v64, 0x37800000, v69
	v_cndmask_b32_e32 v69, v69, v64, vcc
	v_cmp_class_f32_e32 vcc, v68, v71
	s_nop 1
	v_cndmask_b32_e32 v68, v69, v68, vcc
	v_div_scale_f32 v69, s[6:7], v68, v68, 1.0
	v_rcp_f32_e32 v64, v69
	s_nop 0
	v_fma_f32 v65, -v69, v64, 1.0
	v_fmac_f32_e32 v64, v65, v64
	v_div_scale_f32 v65, vcc, 1.0, v68, 1.0
	v_mul_f32_e32 v66, v65, v64
	v_fma_f32 v67, -v69, v66, v65
	v_fmac_f32_e32 v66, v67, v64
	v_fma_f32 v69, -v69, v66, v65
	v_div_fmas_f32 v69, v69, v64, v66
	v_div_fixup_f32 v68, v69, v68, 1.0
	v_mul_f32_e32 v40, v40, v68
	v_mul_f32_e32 v41, v41, v68
	v_mul_f32_e32 v42, v42, v68
	v_mul_f32_e32 v43, v43, v68
	v_mul_f32_e32 v40, v0, v40
	v_mul_f32_e32 v41, v1, v41
	v_mul_f32_e32 v42, v2, v42
	v_mul_f32_e32 v43, v3, v43
	global_store_dwordx4 v80, v[40:43], s[0:1]
	v_mul_f32_e32 v44, v44, v68
	v_mul_f32_e32 v45, v45, v68
	v_mul_f32_e32 v46, v46, v68
	v_mul_f32_e32 v47, v47, v68
	v_mul_f32_e32 v44, v4, v44
	v_mul_f32_e32 v45, v5, v45
	v_mul_f32_e32 v46, v6, v46
	v_mul_f32_e32 v47, v7, v47
	global_store_dwordx4 v80, v[44:47], s[0:1] offset:1024
	v_mul_f32_e32 v48, v48, v68
	v_mul_f32_e32 v49, v49, v68
	v_mul_f32_e32 v50, v50, v68
	v_mul_f32_e32 v51, v51, v68
	v_mul_f32_e32 v48, v8, v48
	v_mul_f32_e32 v49, v9, v49
	v_mul_f32_e32 v50, v10, v50
	v_mul_f32_e32 v51, v11, v51
	global_store_dwordx4 v80, v[48:51], s[0:1] offset:2048
	v_mul_f32_e32 v52, v52, v68
	v_mul_f32_e32 v53, v53, v68
	v_mul_f32_e32 v54, v54, v68
	v_mul_f32_e32 v55, v55, v68
	v_mul_f32_e32 v52, v12, v52
	v_mul_f32_e32 v53, v13, v53
	v_mul_f32_e32 v54, v14, v54
	v_mul_f32_e32 v55, v15, v55
	global_store_dwordx4 v80, v[52:55], s[0:1] offset:3072
	s_add_i32 s11, s11, 1
	s_cmp_ge_u32 s11, s9
	s_cbranch_scc1 .LBB0_806
; __device__ __forceinline__ float bf_lo(unsigned w) { return __uint_as_float(w << 16); }
; __device__ __forceinline__ float bf_hi(unsigned w) { return __uint_as_float(w & 0xffff0000u); }
; __device__ __forceinline__ void phase4(const Params& P, int lane, int wave) {
;     ...
; #pragma unroll
;         for (int j = 0; j < 4; ++j) {
;             r[j][0] = v[j][0] + bf_lo(mv[j].x); r[j][1] = v[j][1] + bf_hi(mv[j].x); r[j][2] = v[j][2] + bf_lo(mv[j].y); r[j][3] = v[j][3] + bf_hi(mv[j].y);
;             ss += (r[j][0] * r[j][0] + r[j][1] * r[j][1]) + (r[j][2] * r[j][2] + r[j][3] * r[j][3]);
;         }
;         const int mn = m + NGW;
;         if (mn < MT) {
;             const float* xrow = (mn < MP) ? P.xp + (size_t)mn * 1024 : P.xs + (size_t)(mn - MP) * 1024;
; #pragma unroll
;             for (int j = 0; j < 4; ++j) { v[j] = *(const f32x4*)(xrow + 4 * lane + 256 * j); mv[j] = *(const u32x2*)(mo + (size_t)mn * 1024 + 4 * lane + 256 * j); }
;         }
;         ss = wave_sum(ss);
;         const float rstd = 1.0f / sqrtf(ss * (1.0f / 1024.0f) + RMS_EPS);
;         float* row = P.out + (size_t)m * 1024;
; #pragma unroll
;         for (int j = 0; j < 4; ++j) *(f32x4*)(row + 4 * lane + 256 * j) = r[j] * rstd * g4[j];
;     }
	s_add_i32 s20, s11, 2
	s_min_u32 s20, s20, s10
	s_mul_i32 s16, s20, s84
	s_add_i32 s16, s16, s8
	s_lshl_b32 s17, s16, 11
	s_add_u32 s14, s4, s17
	s_addc_u32 s15, s5, 0
	s_add_i32 s18, s16, 0xffff0000
	s_cmp_lt_u32 s16, 0x10000
	s_cselect_b32 s18, s16, s18
	s_cselect_b32 s12, s68, s70
	s_cselect_b32 s13, s69, s71
	s_lshr_b32 s19, s18, 20
	s_lshl_b32 s18, s18, 12
	s_add_u32 s12, s12, s18
	s_addc_u32 s13, s13, s19
	global_load_dwordx4 v[40:43], v80, s[12:13]
	global_load_dwordx4 v[44:47], v80, s[12:13] offset:1024
	global_load_dwordx4 v[48:51], v80, s[12:13] offset:2048
	global_load_dwordx4 v[52:55], v80, s[12:13] offset:3072
	global_load_dwordx2 v[56:57], v81, s[14:15]
	global_load_dwordx2 v[58:59], v81, s[14:15] offset:512
	global_load_dwordx2 v[60:61], v81, s[14:15] offset:1024
	global_load_dwordx2 v[62:63], v81, s[14:15] offset:1536
	s_mul_i32 s16, s11, s84
	s_add_i32 s16, s16, s8
	s_lshr_b32 s19, s16, 20
	s_lshl_b32 s18, s16, 12
	s_add_u32 s0, s90, s18
	s_addc_u32 s1, s91, s19
	s_waitcnt vmcnt(16)
	v_lshlrev_b32_e32 v64, 16, v104
	v_and_b32_e32 v65, 0xffff0000, v104
	v_add_f32_e32 v88, v88, v64
	v_add_f32_e32 v89, v89, v65
	v_lshlrev_b32_e32 v64, 16, v105
	v_and_b32_e32 v65, 0xffff0000, v105
	v_add_f32_e32 v90, v90, v64
	v_add_f32_e32 v91, v91, v65
	v_lshlrev_b32_e32 v64, 16, v106
	v_and_b32_e32 v65, 0xffff0000, v106
	v_add_f32_e32 v92, v92, v64
	v_add_f32_e32 v93, v93, v65
	v_lshlrev_b32_e32 v64, 16, v107
	v_and_b32_e32 v65, 0xffff0000, v107
	v_add_f32_e32 v94, v94, v64
	v_add_f32_e32 v95, v95, v65
	v_lshlrev_b32_e32 v64, 16, v108
	v_and_b32_e32 v65, 0xffff0000, v108
	v_add_f32_e32 v96, v96, v64
	v_add_f32_e32 v97, v97, v65
	v_lshlrev_b32_e32 v64, 16, v109
	v_and_b32_e32 v65, 0xffff0000, v109
	v_add_f32_e32 v98, v98, v64
	v_add_f32_e32 v99, v99, v65
	v_lshlrev_b32_e32 v64, 16, v110
	v_and_b32_e32 v65, 0xffff0000, v110
	v_add_f32_e32 v100, v100, v64
	v_add_f32_e32 v101, v101, v65
	v_lshlrev_b32_e32 v64, 16, v111
	v_and_b32_e32 v65, 0xffff0000, v111
	v_add_f32_e32 v102, v102, v64
	v_add_f32_e32 v103, v103, v65
	v_mul_f32_e32 v64, v88, v88
	v_mul_f32_e32 v65, v89, v89
	v_mul_f32_e32 v66, v90, v90
	v_mul_f32_e32 v67, v91, v91
	v_add_f32_e32 v64, v64, v65
	v_add_f32_e32 v66, v66, v67
	v_add_f32_e32 v68, v64, v66
	v_mul_f32_e32 v64, v92, v92
	v_mul_f32_e32 v65, v93, v93
	v_mul_f32_e32 v66, v94, v94
	v_mul_f32_e32 v67, v95, v95
	v_add_f32_e32 v64, v64, v65
	v_add_f32_e32 v66, v66, v67
	v_add_f32_e32 v64, v64, v66
	v_add_f32_e32 v68, v68, v64
	v_mul_f32_e32 v64, v96, v96
	v_mul_f32_e32 v65, v97, v97
	v_mul_f32_e32 v66, v98, v98
	v_mul_f32_e32 v67, v99, v99
	v_add_f32_e32 v64, v64, v65
	v_add_f32_e32 v66, v66, v67
	v_add_f32_e32 v64, v64, v66
	v_add_f32_e32 v68, v68, v64
	v_mul_f32_e32 v64, v100, v100
	v_mul_f32_e32 v65, v101, v101
	v_mul_f32_e32 v66, v102, v102
	v_mul_f32_e32 v67, v103, v103
	v_add_f32_e32 v64, v64, v65
	v_add_f32_e32 v66, v66, v67
	v_add_f32_e32 v64, v64, v66
	v_add_f32_e32 v68, v68, v64
	ds_bpermute_b32 v69, v72, v68
	s_waitcnt lgkmcnt(0)
	v_add_f32_e32 v68, v68, v69
	ds_bpermute_b32 v69, v73, v68
	s_waitcnt lgkmcnt(0)
	v_add_f32_e32 v68, v68, v69
	ds_bpermute_b32 v69, v74, v68
	s_waitcnt lgkmcnt(0)
	v_add_f32_e32 v68, v68, v69
	ds_bpermute_b32 v69, v75, v68
	s_waitcnt lgkmcnt(0)
	v_add_f32_e32 v68, v68, v69
	ds_bpermute_b32 v69, v76, v68
	s_waitcnt lgkmcnt(0)
	v_add_f32_e32 v68, v68, v69
	ds_bpermute_b32 v69, v77, v68
	s_waitcnt lgkmcnt(0)
	v_add_f32_e32 v68, v68, v69
	v_fmamk_f32 v68, v68, 0x3a800000, v70
	v_mul_f32_e32 v69, 0x4f800000, v68
	v_cmp_gt_f32_e32 vcc, s2, v68
	s_nop 1
	v_cndmask_b32_e32 v68, v68, v69, vcc
	v_sqrt_f32_e32 v69, v68
	s_nop 0
	v_add_u32_e32 v64, -1, v69
	v_fma_f32 v65, -v64, v69, v68
	v_cmp_ge_f32_e64 s[6:7], 0, v65
	v_add_u32_e32 v65, 1, v69
	s_nop 0
	v_cndmask_b32_e64 v64, v69, v64, s[6:7]
	v_fma_f32 v69, -v65, v69, v68
	v_cmp_lt_f32_e64 s[6:7], 0, v69
	s_nop 1
	v_cndmask_b32_e64 v69, v64, v65, s[6:7]
	v_mul_f32_e32 v64, 0x37800000, v69
	v_cndmask_b32_e32 v69, v69, v64, vcc
	v_cmp_class_f32_e32 vcc, v68, v71
	s_nop 1
	v_cndmask_b32_e32 v68, v69, v68, vcc
	v_div_scale_f32 v69, s[6:7], v68, v68, 1.0
	v_rcp_f32_e32 v64, v69
	s_nop 0
	v_fma_f32 v65, -v69, v64, 1.0
	v_fmac_f32_e32 v64, v65, v64
	v_div_scale_f32 v65, vcc, 1.0, v68, 1.0
	v_mul_f32_e32 v66, v65, v64
	v_fma_f32 v67, -v69, v66, v65
	v_fmac_f32_e32 v66, v67, v64
	v_fma_f32 v69, -v69, v66, v65
	v_div_fmas_f32 v69, v69, v64, v66
	v_div_fixup_f32 v68, v69, v68, 1.0
	v_mul_f32_e32 v88, v88, v68
	v_mul_f32_e32 v89, v89, v68
	v_mul_f32_e32 v90, v90, v68
	v_mul_f32_e32 v91, v91, v68
	v_mul_f32_e32 v88, v0, v88
	v_mul_f32_e32 v89, v1, v89
	v_mul_f32_e32 v90, v2, v90
	v_mul_f32_e32 v91, v3, v91
	global_store_dwordx4 v80, v[88:91], s[0:1]
	v_mul_f32_e32 v92, v92, v68
	v_mul_f32_e32 v93, v93, v68
	v_mul_f32_e32 v94, v94, v68
	v_mul_f32_e32 v95, v95, v68
	v_mul_f32_e32 v92, v4, v92
	v_mul_f32_e32 v93, v5, v93
	v_mul_f32_e32 v94, v6, v94
	v_mul_f32_e32 v95, v7, v95
	global_store_dwordx4 v80, v[92:95], s[0:1] offset:1024
	v_mul_f32_e32 v96, v96, v68
	v_mul_f32_e32 v97, v97, v68
	v_mul_f32_e32 v98, v98, v68
	v_mul_f32_e32 v99, v99, v68
	v_mul_f32_e32 v96, v8, v96
	v_mul_f32_e32 v97, v9, v97
	v_mul_f32_e32 v98, v10, v98
	v_mul_f32_e32 v99, v11, v99
	global_store_dwordx4 v80, v[96:99], s[0:1] offset:2048
	v_mul_f32_e32 v100, v100, v68
	v_mul_f32_e32 v101, v101, v68
	v_mul_f32_e32 v102, v102, v68
	v_mul_f32_e32 v103, v103, v68
	v_mul_f32_e32 v100, v12, v100
	v_mul_f32_e32 v101, v13, v101
	v_mul_f32_e32 v102, v14, v102
	v_mul_f32_e32 v103, v15, v103
	global_store_dwordx4 v80, v[100:103], s[0:1] offset:3072
	s_add_i32 s11, s11, 1
	s_cmp_ge_u32 s11, s9
	s_cbranch_scc1 .LBB0_806
	s_branch .Lp4_loop
